# GEMM1 epilogue stores write-through (sc1) so the barrier's L2 writeback is short; first two vmcnt waits per tile relaxed to 24
# speedup vs baseline: 1.0083x; 1.0051x over previous
; __device__ __forceinline__ unsigned cvtpk(float lo, float hi) { f32x2_t v = {lo, hi}; f16x2_t b = __builtin_convertvector(v, f16x2_t); return __builtin_bit_cast(unsigned, b); }
;     __device__ __forceinline__ void operator()(const f32x4 (&acc)[2][2][4][2], const Unit& u, int wr, int wc, int fr, int fq) const {
;     ...
; #pragma unroll
;         for (int ai = 0; ai < 2; ++ai)
; #pragma unroll
;             for (int m = 0; m < 4; ++m) { const int row = row0 + ai * HALF + m * 16; const int bl = row >> 12, t = row & 4095;
; #pragma unroll
;                 for (int bj = 0; bj < 2; ++bj) { const f32x4 v0 = acc[ai][bj][m][0] * rs[ai][m], v1 = acc[ai][bj][m][1] * rs[ai][m];
;                     u32x4 w; w.x = cvtpk(v0[0], v0[1]); w.y = cvtpk(v0[2], v0[3]); w.z = cvtpk(v1[0], v1[1]); w.w = cvtpk(v1[2], v1[3]);
;                     const int ct = bj * HALF + wc * 32 + 8 * fq;
;                     bf16_t* dst;
;                     if (pn < 18) { const int sect = pn / 6, hh = (pn - sect * 6) * 4 + (ct >> 6), dsh = 2 * (hh >> 3); const int idx = ((t & ((1 << dsh) - 1)) << (12 - dsh)) + (t >> dsh);
;                         dst = P + PL_A + ((size_t)((bl * 3 + sect) * 24 + hh) * 4096 + idx) * 64 + (ct & 63); }
;                     else if (pn < 22) { const int qk = (pn - 18) >> 1, head = ((pn - 18) & 1) * 2 + (ct >> 7);
;                         dst = P + PL_QR + (size_t)qk * PL_QK_SZ + ((size_t)(bl * 4 + head) * 4096 + t) * 128 + (ct & 127); }
;                     else if (pn < 30) { const int vg = (pn - 22) >> 2, head = (pn - 22) & 3;
;                         dst = P + PL_VR + (size_t)vg * PL_VG_SZ + ((size_t)(bl * 4 + head) * 4096 + t) * 256 + ct; }
;                     else dst = G + (size_t)row * 2048 + (pn - 30) * 256 + ct;
;                     *(u32x4*)dst = w; } }
.Lepi1_go:
	s_add_i32 s27, s55, s57
	s_waitcnt lgkmcnt(0)
	v_pk_mul_f32 v[126:127], v[126:127], v[150:151] op_sel_hi:[1,0]
	v_pk_mul_f32 v[128:129], v[128:129], v[150:151] op_sel_hi:[1,0]
	v_pk_mul_f32 v[122:123], v[122:123], v[150:151] op_sel_hi:[1,0]
	v_pk_mul_f32 v[124:125], v[124:125], v[150:151] op_sel_hi:[1,0]
	v_cvt_pk_f16_f32 v126, v126, v127
	v_cvt_pk_f16_f32 v127, v128, v129
	v_cvt_pk_f16_f32 v128, v122, v123
	v_cvt_pk_f16_f32 v129, v124, v125
	v_mov_b32_e32 v184, v183
	global_store_dwordx4 v184, v[126:129], s[100:101] sc1
	v_pk_mul_f32 v[110:111], v[110:111], v[150:151] op_sel:[0,1] op_sel_hi:[1,1]
	v_pk_mul_f32 v[112:113], v[112:113], v[150:151] op_sel:[0,1] op_sel_hi:[1,1]
	v_pk_mul_f32 v[106:107], v[106:107], v[150:151] op_sel:[0,1] op_sel_hi:[1,1]
	v_pk_mul_f32 v[108:109], v[108:109], v[150:151] op_sel:[0,1] op_sel_hi:[1,1]
	v_cvt_pk_f16_f32 v110, v110, v111
	v_cvt_pk_f16_f32 v111, v112, v113
	v_cvt_pk_f16_f32 v112, v106, v107
	v_cvt_pk_f16_f32 v113, v108, v109
	v_add_u32_e32 v185, s45, v184
	global_store_dwordx4 v185, v[110:113], s[100:101] sc1
	v_pk_mul_f32 v[94:95], v[94:95], v[148:149] op_sel_hi:[1,0]
	v_pk_mul_f32 v[96:97], v[96:97], v[148:149] op_sel_hi:[1,0]
	v_pk_mul_f32 v[90:91], v[90:91], v[148:149] op_sel_hi:[1,0]
	v_pk_mul_f32 v[92:93], v[92:93], v[148:149] op_sel_hi:[1,0]
	v_cvt_pk_f16_f32 v94, v94, v95
	v_cvt_pk_f16_f32 v95, v96, v97
	v_cvt_pk_f16_f32 v96, v90, v91
	v_cvt_pk_f16_f32 v97, v92, v93
	v_add_u32_e32 v186, s45, v185
	global_store_dwordx4 v186, v[94:97], s[100:101] sc1
	v_pk_mul_f32 v[78:79], v[78:79], v[148:149] op_sel:[0,1] op_sel_hi:[1,1]
	v_pk_mul_f32 v[80:81], v[80:81], v[148:149] op_sel:[0,1] op_sel_hi:[1,1]
	v_pk_mul_f32 v[74:75], v[74:75], v[148:149] op_sel:[0,1] op_sel_hi:[1,1]
	v_pk_mul_f32 v[76:77], v[76:77], v[148:149] op_sel:[0,1] op_sel_hi:[1,1]
	v_cvt_pk_f16_f32 v78, v78, v79
	v_cvt_pk_f16_f32 v79, v80, v81
	v_cvt_pk_f16_f32 v80, v74, v75
	v_cvt_pk_f16_f32 v81, v76, v77
	v_add_u32_e32 v187, s45, v186
	global_store_dwordx4 v187, v[78:81], s[100:101] sc1
	v_pk_mul_f32 v[118:119], v[118:119], v[150:151] op_sel_hi:[1,0]
	v_pk_mul_f32 v[120:121], v[120:121], v[150:151] op_sel_hi:[1,0]
	v_pk_mul_f32 v[114:115], v[114:115], v[150:151] op_sel_hi:[1,0]
	v_pk_mul_f32 v[116:117], v[116:117], v[150:151] op_sel_hi:[1,0]
	v_cvt_pk_f16_f32 v118, v118, v119
	v_cvt_pk_f16_f32 v119, v120, v121
	v_cvt_pk_f16_f32 v120, v114, v115
	v_cvt_pk_f16_f32 v121, v116, v117
	v_add_u32_e32 v184, s57, v183
	global_store_dwordx4 v184, v[118:121], s[100:101] sc1
	v_pk_mul_f32 v[102:103], v[102:103], v[150:151] op_sel:[0,1] op_sel_hi:[1,1]
	v_pk_mul_f32 v[104:105], v[104:105], v[150:151] op_sel:[0,1] op_sel_hi:[1,1]
	v_pk_mul_f32 v[98:99], v[98:99], v[150:151] op_sel:[0,1] op_sel_hi:[1,1]
	v_pk_mul_f32 v[100:101], v[100:101], v[150:151] op_sel:[0,1] op_sel_hi:[1,1]
	v_cvt_pk_f16_f32 v102, v102, v103
	v_cvt_pk_f16_f32 v103, v104, v105
	v_cvt_pk_f16_f32 v104, v98, v99
	v_cvt_pk_f16_f32 v105, v100, v101
	v_add_u32_e32 v185, s45, v184
	global_store_dwordx4 v185, v[102:105], s[100:101] sc1
	v_pk_mul_f32 v[86:87], v[86:87], v[148:149] op_sel_hi:[1,0]
	v_pk_mul_f32 v[88:89], v[88:89], v[148:149] op_sel_hi:[1,0]
	v_pk_mul_f32 v[82:83], v[82:83], v[148:149] op_sel_hi:[1,0]
	v_pk_mul_f32 v[84:85], v[84:85], v[148:149] op_sel_hi:[1,0]
	v_cvt_pk_f16_f32 v86, v86, v87
	v_cvt_pk_f16_f32 v87, v88, v89
	v_cvt_pk_f16_f32 v88, v82, v83
	v_cvt_pk_f16_f32 v89, v84, v85
	v_add_u32_e32 v186, s45, v185
	global_store_dwordx4 v186, v[86:89], s[100:101] sc1
	v_pk_mul_f32 v[70:71], v[70:71], v[148:149] op_sel:[0,1] op_sel_hi:[1,1]
	v_pk_mul_f32 v[72:73], v[72:73], v[148:149] op_sel:[0,1] op_sel_hi:[1,1]
	v_pk_mul_f32 v[66:67], v[66:67], v[148:149] op_sel:[0,1] op_sel_hi:[1,1]
	v_pk_mul_f32 v[68:69], v[68:69], v[148:149] op_sel:[0,1] op_sel_hi:[1,1]
	v_cvt_pk_f16_f32 v70, v70, v71
	v_cvt_pk_f16_f32 v71, v72, v73
	v_cvt_pk_f16_f32 v72, v66, v67
	v_cvt_pk_f16_f32 v73, v68, v69
	v_add_u32_e32 v187, s45, v186
	global_store_dwordx4 v187, v[70:73], s[100:101] sc1
	v_pk_mul_f32 v[62:63], v[62:63], v[146:147] op_sel_hi:[1,0]
	v_pk_mul_f32 v[64:65], v[64:65], v[146:147] op_sel_hi:[1,0]
	v_pk_mul_f32 v[58:59], v[58:59], v[146:147] op_sel_hi:[1,0]
; __device__ __forceinline__ unsigned cvtpk(float lo, float hi) { f32x2_t v = {lo, hi}; f16x2_t b = __builtin_convertvector(v, f16x2_t); return __builtin_bit_cast(unsigned, b); }
; #define PG8_BAR __builtin_amdgcn_s_barrier()
;     __device__ __forceinline__ void operator()(const f32x4 (&acc)[2][2][4][2], const Unit& u, int wr, int wc, int fr, int fq) const {
;     ...
;                 for (int bj = 0; bj < 2; ++bj) { const f32x4 v0 = acc[ai][bj][m][0] * rs[ai][m], v1 = acc[ai][bj][m][1] * rs[ai][m];
;                     u32x4 w; w.x = cvtpk(v0[0], v0[1]); w.y = cvtpk(v0[2], v0[3]); w.z = cvtpk(v1[0], v1[1]); w.w = cvtpk(v1[2], v1[3]);
;                     const int ct = bj * HALF + wc * 32 + 8 * fq;
;                     bf16_t* dst;
;                     if (pn < 18) { const int sect = pn / 6, hh = (pn - sect * 6) * 4 + (ct >> 6), dsh = 2 * (hh >> 3); const int idx = ((t & ((1 << dsh) - 1)) << (12 - dsh)) + (t >> dsh);
;                         dst = P + PL_A + ((size_t)((bl * 3 + sect) * 24 + hh) * 4096 + idx) * 64 + (ct & 63); }
;                     else if (pn < 22) { const int qk = (pn - 18) >> 1, head = ((pn - 18) & 1) * 2 + (ct >> 7);
;                         dst = P + PL_QR + (size_t)qk * PL_QK_SZ + ((size_t)(bl * 4 + head) * 4096 + t) * 128 + (ct & 127); }
;                     else if (pn < 30) { const int vg = (pn - 22) >> 2, head = (pn - 22) & 3;
;                         dst = P + PL_VR + (size_t)vg * PL_VG_SZ + ((size_t)(bl * 4 + head) * 4096 + t) * 256 + ct; }
;                     else dst = G + (size_t)row * 2048 + (pn - 30) * 256 + ct;
;                     *(u32x4*)dst = w; } }
; template <class Epi, class Sched, bool ALIGN_EPI = false, bool SP2 = false>
; __device__ __forceinline__ void gemm_phase(PG8_LAS unsigned char* lds, const Gemm g, const Sched& S, const Epi& E) {
;     ...
;         if (!has_next) break;
; #pragma unroll
;         for (int a = 0; a < 2; ++a)
; #pragma unroll
;             for (int b = 0; b < 2; ++b)
; #pragma unroll
;                 for (int m = 0; m < 4; ++m)
; #pragma unroll
;                     for (int n = 0; n < 2; ++n) acc[a][b][m][n] = (f32x4){0.f, 0.f, 0.f, 0.f};
;         cur = nxt; cA = nA; cB = nB; ++ui;
;         if constexpr (ALIGN_EPI) { if (wr == 1) PG8_BAR; }
	v_pk_mul_f32 v[60:61], v[60:61], v[146:147] op_sel_hi:[1,0]
	v_cvt_pk_f16_f32 v62, v62, v63
	v_cvt_pk_f16_f32 v63, v64, v65
	v_cvt_pk_f16_f32 v64, v58, v59
	v_cvt_pk_f16_f32 v65, v60, v61
	v_add_u32_e32 v184, s55, v183
	global_store_dwordx4 v184, v[62:65], s[100:101] sc1
	v_pk_mul_f32 v[46:47], v[46:47], v[146:147] op_sel:[0,1] op_sel_hi:[1,1]
	v_pk_mul_f32 v[48:49], v[48:49], v[146:147] op_sel:[0,1] op_sel_hi:[1,1]
	v_pk_mul_f32 v[42:43], v[42:43], v[146:147] op_sel:[0,1] op_sel_hi:[1,1]
	v_pk_mul_f32 v[44:45], v[44:45], v[146:147] op_sel:[0,1] op_sel_hi:[1,1]
	v_cvt_pk_f16_f32 v46, v46, v47
	v_cvt_pk_f16_f32 v47, v48, v49
	v_cvt_pk_f16_f32 v48, v42, v43
	v_cvt_pk_f16_f32 v49, v44, v45
	v_add_u32_e32 v185, s45, v184
	global_store_dwordx4 v185, v[46:49], s[100:101] sc1
	v_pk_mul_f32 v[30:31], v[30:31], v[142:143] op_sel_hi:[1,0]
	v_pk_mul_f32 v[32:33], v[32:33], v[142:143] op_sel_hi:[1,0]
	v_pk_mul_f32 v[26:27], v[26:27], v[142:143] op_sel_hi:[1,0]
	v_pk_mul_f32 v[28:29], v[28:29], v[142:143] op_sel_hi:[1,0]
	v_cvt_pk_f16_f32 v30, v30, v31
	v_cvt_pk_f16_f32 v31, v32, v33
	v_cvt_pk_f16_f32 v32, v26, v27
	v_cvt_pk_f16_f32 v33, v28, v29
	v_add_u32_e32 v186, s45, v185
	global_store_dwordx4 v186, v[30:33], s[100:101] sc1
	v_pk_mul_f32 v[14:15], v[14:15], v[142:143] op_sel:[0,1] op_sel_hi:[1,1]
	v_pk_mul_f32 v[16:17], v[16:17], v[142:143] op_sel:[0,1] op_sel_hi:[1,1]
	v_pk_mul_f32 v[10:11], v[10:11], v[142:143] op_sel:[0,1] op_sel_hi:[1,1]
	v_pk_mul_f32 v[12:13], v[12:13], v[142:143] op_sel:[0,1] op_sel_hi:[1,1]
	v_cvt_pk_f16_f32 v14, v14, v15
	v_cvt_pk_f16_f32 v15, v16, v17
	v_cvt_pk_f16_f32 v16, v10, v11
	v_cvt_pk_f16_f32 v17, v12, v13
	v_add_u32_e32 v187, s45, v186
	global_store_dwordx4 v187, v[14:17], s[100:101] sc1
	v_pk_mul_f32 v[54:55], v[54:55], v[146:147] op_sel_hi:[1,0]
	v_pk_mul_f32 v[56:57], v[56:57], v[146:147] op_sel_hi:[1,0]
	v_pk_mul_f32 v[50:51], v[50:51], v[146:147] op_sel_hi:[1,0]
	v_pk_mul_f32 v[52:53], v[52:53], v[146:147] op_sel_hi:[1,0]
	v_cvt_pk_f16_f32 v54, v54, v55
	v_cvt_pk_f16_f32 v55, v56, v57
	v_cvt_pk_f16_f32 v56, v50, v51
	v_cvt_pk_f16_f32 v57, v52, v53
	v_add_u32_e32 v184, s27, v183
	global_store_dwordx4 v184, v[54:57], s[100:101] sc1
	v_pk_mul_f32 v[38:39], v[38:39], v[146:147] op_sel:[0,1] op_sel_hi:[1,1]
	v_pk_mul_f32 v[40:41], v[40:41], v[146:147] op_sel:[0,1] op_sel_hi:[1,1]
	v_pk_mul_f32 v[34:35], v[34:35], v[146:147] op_sel:[0,1] op_sel_hi:[1,1]
	v_pk_mul_f32 v[36:37], v[36:37], v[146:147] op_sel:[0,1] op_sel_hi:[1,1]
	v_cvt_pk_f16_f32 v38, v38, v39
	v_cvt_pk_f16_f32 v39, v40, v41
	v_cvt_pk_f16_f32 v40, v34, v35
	v_cvt_pk_f16_f32 v41, v36, v37
	v_add_u32_e32 v185, s45, v184
	global_store_dwordx4 v185, v[38:41], s[100:101] sc1
	v_pk_mul_f32 v[22:23], v[22:23], v[142:143] op_sel_hi:[1,0]
	v_pk_mul_f32 v[24:25], v[24:25], v[142:143] op_sel_hi:[1,0]
	v_pk_mul_f32 v[18:19], v[18:19], v[142:143] op_sel_hi:[1,0]
	v_pk_mul_f32 v[20:21], v[20:21], v[142:143] op_sel_hi:[1,0]
	v_cvt_pk_f16_f32 v22, v22, v23
	v_cvt_pk_f16_f32 v23, v24, v25
	v_cvt_pk_f16_f32 v24, v18, v19
	v_cvt_pk_f16_f32 v25, v20, v21
	v_add_u32_e32 v186, s45, v185
	global_store_dwordx4 v186, v[22:25], s[100:101] sc1
	v_pk_mul_f32 v[6:7], v[6:7], v[142:143] op_sel:[0,1] op_sel_hi:[1,1]
	v_pk_mul_f32 v[8:9], v[8:9], v[142:143] op_sel:[0,1] op_sel_hi:[1,1]
	v_pk_mul_f32 v[2:3], v[2:3], v[142:143] op_sel:[0,1] op_sel_hi:[1,1]
	v_pk_mul_f32 v[4:5], v[4:5], v[142:143] op_sel:[0,1] op_sel_hi:[1,1]
	v_cvt_pk_f16_f32 v6, v6, v7
	v_cvt_pk_f16_f32 v7, v8, v9
	v_cvt_pk_f16_f32 v8, v2, v3
	v_cvt_pk_f16_f32 v9, v4, v5
	v_add_u32_e32 v187, s45, v186
	global_store_dwordx4 v187, v[6:9], s[100:101] sc1
	s_mov_b32 s30, 0x8000
	s_mov_b32 s31, s65
	v_readlane_b32 s76, v253, 5
	v_readlane_b32 s77, v253, 6
	v_readlane_b32 s78, v253, 7
	v_readlane_b32 s79, v253, 8
	s_movk_i32 s80, 0x4000
	s_movk_i32 s81, 0x1000
	v_readlane_b32 s84, v255, 30
	s_mov_b32 s85, 0x11000
	s_mov_b32 s70, 1
	s_andn2_b64 vcc, exec, s[38:39]
	s_mov_b64 s[24:25], -1
	s_mov_b32 s56, 0x21000
	s_cbranch_vccnz .LBB0_149
	v_readlane_b32 s24, v255, 49
	v_readlane_b32 s25, v255, 50
	s_andn2_b64 vcc, exec, s[24:25]
	s_cbranch_vccnz .LBB0_148
	s_barrier
	s_branch .LBB0_148
